# P2: half of the workgroups (blockIdx bit 3) run qkprep before ssd_states so the memory-bound and compute-bound halves overlap across CUs
# speedup vs baseline: 1.0220x; 1.0026x over previous
.LBB0_335:
	s_cmp_lt_i32 s86, 3
	s_cselect_b64 s[0:1], -1, 0
	s_cmp_gt_i32 s87, 2
	s_cselect_b64 s[2:3], -1, 0
	s_and_b64 s[0:1], s[0:1], s[2:3]
	s_andn2_b64 vcc, exec, s[0:1]
	s_cbranch_vccnz .LBB0_515
	s_mov_b32 s94, 2
	s_bitcmp1_b32 s33, 3
	s_cbranch_scc0 .Lmy_p2_pre
	s_mov_b32 s94, 0
.Lmy_p2_pre:
	s_add_u32 s12, s84, 0x9400000
	s_addc_u32 s13, s85, 0
	s_cmp_eq_u32 s94, 0
	s_cbranch_scc1 .LBB0_388
	s_cmpk_gt_i32 s33, 0xff
	s_cbranch_scc1 .LBB0_388
	s_add_u32 s14, s84, 0x5000000
	s_addc_u32 s15, s85, 0
	s_add_u32 s16, s84, 0xf400000
	s_addc_u32 s17, s85, 0
	v_lshrrev_b32_e32 v4, 2, v158
	s_add_u32 s18, s84, 0x5099000
	v_and_b32_e32 v144, 0xf0, v4
	v_lshlrev_b32_e32 v4, 6, v158
	s_addc_u32 s19, s85, 0
	v_and_b32_e32 v2, 0x380, v158
	s_add_i32 s10, 0, 0x19800
	s_add_i32 s22, 0, 0x1b000
	v_and_b32_e32 v4, 0x600, v4
	s_add_i32 s23, 0, 0x11000
	v_lshl_add_u32 v140, v2, 2, s10
	v_and_b32_e32 v2, 63, v158
	v_add_u32_e32 v148, s22, v4
	s_movk_i32 s22, 0x880
	v_mov_b32_e32 v4, s23
	v_lshrrev_b32_e32 v80, 7, v158
	v_cmp_gt_u32_e64 s[4:5], 48, v2
	v_cmp_gt_u32_e64 s[6:7], 32, v2
	v_cmp_lt_u32_e64 s[8:9], 31, v2
	v_lshlrev_b32_e32 v145, 3, v2
	v_mad_u32_u24 v149, v2, s22, 0
	v_mad_u32_u24 v2, v2, s22, v4
	v_lshrrev_b32_e32 v6, 1, v158
	v_and_b32_e32 v0, 31, v158
	v_bfe_u32 v1, v158, 5, 1
	v_add_u32_e32 v150, 0xfffef220, v2
	v_add_u32_e32 v151, 0xfffef330, v2
	v_add_u32_e32 v152, 0xfffef440, v2
	v_add_u32_e32 v153, 0xfffef550, v2
	v_add_u32_e32 v154, 0xfffef660, v2
	v_add_u32_e32 v155, 0xfffef770, v2
	v_lshlrev_b32_e32 v2, 6, v80
	v_and_b32_e32 v6, 32, v6
	s_movk_i32 s20, 0x78
	v_or3_b32 v2, v6, v2, v0
	v_lshlrev_b32_e32 v8, 3, v1
	v_bitop3_b32 v10, v2, v8, s20 bitop3:0x6c
	v_lshlrev_b32_e32 v11, 1, v10
	v_bitop3_b32 v10, v8, v158, 24 bitop3:0x78
	v_lshlrev_b32_e32 v13, 1, v10
	v_or_b32_e32 v10, 32, v0
	s_movk_i32 s22, 0x110
	v_bitop3_b32 v10, v10, v8, 56 bitop3:0x6c
	v_mad_u32_u24 v7, v2, s22, 0
	v_mad_u32_u24 v9, v0, s22, v4
	v_lshlrev_b32_e32 v17, 1, v10
	v_or_b32_e32 v10, 64, v0
	s_movk_i32 s22, 0x58
	v_bitop3_b32 v10, v10, v8, s22 bitop3:0x6c
	v_lshlrev_b32_e32 v21, 1, v10
	v_or_b32_e32 v10, 0x60, v0
	v_bitop3_b32 v10, v10, v8, s20 bitop3:0x6c
	v_lshlrev_b32_e32 v25, 1, v10
	v_or_b32_e32 v10, 16, v8
	v_and_b32_e32 v4, 24, v158
	v_bitop3_b32 v10, v2, v10, s20 bitop3:0x6c
	v_bitop3_b32 v12, v0, 56, 32 bitop3:0xc8
	v_lshlrev_b32_e32 v27, 1, v10
	v_bitop3_b32 v10, v8, v4, 16 bitop3:0x36
	s_waitcnt lgkmcnt(0)
	v_bitop3_b32 v14, v0, s22, 64 bitop3:0xc8
	v_mov_b32_e32 v16, 0x60
	v_lshlrev_b32_e32 v29, 1, v10
	v_bitop3_b32 v10, v8, v12, 16 bitop3:0x36
	v_bitop3_b32 v16, v0, s20, v16 bitop3:0xc8
	v_lshlrev_b32_e32 v31, 1, v10
	v_bitop3_b32 v10, v8, v14, 16 bitop3:0x36
	v_lshlrev_b32_e32 v32, 1, v10
	v_bitop3_b32 v10, v8, v16, 16 bitop3:0x36
	v_lshlrev_b32_e32 v33, 1, v10
	v_or_b32_e32 v10, 32, v8
	v_bitop3_b32 v10, v2, v10, s20 bitop3:0x6c
	v_lshlrev_b32_e32 v34, 1, v10
	v_bitop3_b32 v10, v8, v4, 32 bitop3:0x36
	v_lshlrev_b32_e32 v35, 1, v10
	v_bitop3_b32 v10, v8, v12, 32 bitop3:0x36
	v_lshlrev_b32_e32 v36, 1, v10
	v_bitop3_b32 v10, v8, v14, 32 bitop3:0x36
	v_lshlrev_b32_e32 v37, 1, v10
	v_bitop3_b32 v10, v8, v16, 32 bitop3:0x36
	v_lshlrev_b32_e32 v38, 1, v10
	v_or_b32_e32 v10, 48, v8
	v_bitop3_b32 v10, v2, v10, s20 bitop3:0x6c
	v_lshlrev_b32_e32 v39, 1, v10
	v_bitop3_b32 v10, v8, v4, 48 bitop3:0x36
	v_lshlrev_b32_e32 v40, 1, v10
	v_bitop3_b32 v10, v8, v12, 48 bitop3:0x36
	v_lshlrev_b32_e32 v41, 1, v10
	v_bitop3_b32 v10, v8, v14, 48 bitop3:0x36
	v_lshlrev_b32_e32 v42, 1, v10
	v_bitop3_b32 v10, v8, v16, 48 bitop3:0x36
	v_lshlrev_b32_e32 v43, 1, v10
	v_or_b32_e32 v10, 64, v8
	v_bitop3_b32 v10, v2, v10, s20 bitop3:0x6c
	v_lshlrev_b32_e32 v44, 1, v10
	v_bitop3_b32 v10, v8, v4, 64 bitop3:0x36
	v_lshlrev_b32_e32 v45, 1, v10
	v_bitop3_b32 v10, v8, v12, 64 bitop3:0x36
	v_lshlrev_b32_e32 v46, 1, v10
	v_bitop3_b32 v10, v8, v14, 64 bitop3:0x36
	v_lshlrev_b32_e32 v47, 1, v10
	v_bitop3_b32 v10, v8, v16, 64 bitop3:0x36
	v_lshlrev_b32_e32 v48, 1, v10
	v_or_b32_e32 v10, 0x50, v8
	s_movk_i32 s23, 0x50
	v_bitop3_b32 v10, v2, v10, s20 bitop3:0x6c
	v_lshlrev_b32_e32 v49, 1, v10
	v_bitop3_b32 v10, v8, v4, s23 bitop3:0x36
	v_lshlrev_b32_e32 v50, 1, v10
	v_bitop3_b32 v10, v8, v12, s23 bitop3:0x36
	v_lshlrev_b32_e32 v51, 1, v10
	v_bitop3_b32 v10, v8, v14, s23 bitop3:0x36
	v_lshlrev_b32_e32 v52, 1, v10
	v_bitop3_b32 v10, v8, v16, s23 bitop3:0x36
	v_lshlrev_b32_e32 v53, 1, v10
	v_or_b32_e32 v10, 0x60, v8
	s_movk_i32 s22, 0x60
	v_bitop3_b32 v10, v2, v10, s20 bitop3:0x6c
	v_lshlrev_b32_e32 v54, 1, v10
	v_bitop3_b32 v10, v8, v4, s22 bitop3:0x36
	v_lshlrev_b32_e32 v55, 1, v10
	v_bitop3_b32 v10, v8, v12, s22 bitop3:0x36
	v_lshlrev_b32_e32 v56, 1, v10
	v_bitop3_b32 v10, v8, v14, s22 bitop3:0x36
	v_lshlrev_b32_e32 v57, 1, v10
	v_bitop3_b32 v10, v8, v16, s22 bitop3:0x36
	v_lshlrev_b32_e32 v58, 1, v10
	v_or_b32_e32 v10, 0x70, v8
	s_movk_i32 s11, 0x70
	v_bitop3_b32 v2, v2, v10, s20 bitop3:0x6c
	v_lshlrev_b32_e32 v59, 1, v2
	v_bitop3_b32 v2, v8, v4, s11 bitop3:0x36
	v_lshlrev_b32_e32 v60, 1, v2
	v_bitop3_b32 v2, v8, v12, s11 bitop3:0x36
	v_lshlrev_b32_e32 v61, 1, v2
	v_bitop3_b32 v2, v8, v14, s11 bitop3:0x36
	v_lshlrev_b32_e32 v62, 1, v2
	v_bitop3_b32 v2, v8, v16, s11 bitop3:0x36
	v_lshlrev_b32_e32 v3, 2, v158
	s_add_i32 s0, 0, 0x1a800
	v_lshlrev_b32_e32 v1, 9, v1
	v_lshlrev_b32_e32 v63, 1, v2
	v_lshlrev_b32_e32 v2, 7, v6
	v_add_u32_e32 v138, s0, v3
	s_add_i32 s0, 0, 0x1a000
	v_or3_b32 v0, v1, v0, v2
	v_lshlrev_b32_e32 v1, 9, v80
	s_movk_i32 s11, 0x1c0
	s_movk_i32 s2, 0x7f
	v_and_b32_e32 v81, 0x7f, v158
	v_add_u32_e32 v139, s10, v3
	v_and_b32_e32 v5, 0x70, v158
	v_add_u32_e32 v142, s0, v3
	v_add_u32_e32 v15, 0x2200, v9
	v_add_u32_e32 v19, 0x4400, v9
	v_add_u32_e32 v23, 0x6600, v9
	v_or_b32_e32 v2, 0x400, v0
	v_or_b32_e32 v4, 0x480, v0
	v_or_b32_e32 v6, 0x500, v0
	v_or_b32_e32 v8, 0x580, v0
	v_or_b32_e32 v10, 0x800, v0
	v_or_b32_e32 v12, 0x880, v0
	v_or_b32_e32 v14, 0x900, v0
	v_or_b32_e32 v16, 0x980, v0
	v_or_b32_e32 v18, 0xc00, v0
	v_or_b32_e32 v20, 0xc80, v0
	v_or_b32_e32 v22, 0xd00, v0
	v_or_b32_e32 v24, 0xd80, v0
	v_or_b32_e32 v26, 0x80, v0
	v_or_b32_e32 v28, 0x100, v0
	v_or_b32_e32 v30, 0x180, v0
	v_and_or_b32 v3, v3, s11, v1
	v_add_u32_e32 v1, 0, v1
	v_mov_b32_e32 v83, 0
	s_mov_b32 s21, 0
	v_bfe_u32 v141, v158, 4, 3
	v_cmp_lt_u32_e64 s[0:1], 15, v81
	v_lshl_add_u32 v143, v81, 2, v140
	v_cmp_eq_u32_e64 s[2:3], s2, v81
	v_add_u32_e32 v146, 0x300, v145
	v_and_b32_e32 v147, 0x78, v145
	s_mov_b32 s29, 0x11000
	v_add_u32_e32 v156, -1, v5
	v_add_u32_e32 v157, s10, v3
	v_add_u32_e32 v160, 0x1a03c, v1
	s_mov_b64 s[22:23], 0x2000
	s_mov_b64 s[24:25], 0x4000
	s_mov_b64 s[26:27], 0x6000
	s_movk_i32 s38, 0x3000
	s_mov_b32 s28, 0xbfb8aa3b
	v_add_u32_e32 v161, v7, v11
	v_add_u32_e32 v162, v9, v13
	v_add_u32_e32 v163, v15, v17
	v_add_u32_e32 v164, v19, v21
	v_add_u32_e32 v165, v23, v25
	v_add_u32_e32 v166, v7, v27
	v_add_u32_e32 v167, v9, v29
	v_add_u32_e32 v168, v15, v31
	v_add_u32_e32 v169, v19, v32
	v_add_u32_e32 v170, v23, v33
	v_add_u32_e32 v171, v7, v34
	v_add_u32_e32 v172, v9, v35
	v_add_u32_e32 v173, v15, v36
	v_add_u32_e32 v174, v19, v37
	v_add_u32_e32 v175, v23, v38
	v_add_u32_e32 v176, v7, v39
	v_add_u32_e32 v177, v9, v40
	v_add_u32_e32 v178, v15, v41
	v_add_u32_e32 v179, v19, v42
	v_add_u32_e32 v180, v23, v43
	v_add_u32_e32 v181, v7, v44
	v_add_u32_e32 v182, v9, v45
	v_add_u32_e32 v183, v15, v46
	v_add_u32_e32 v184, v19, v47
	v_add_u32_e32 v185, v23, v48
	v_add_u32_e32 v186, v7, v49
	v_add_u32_e32 v187, v9, v50
	v_add_u32_e32 v188, v15, v51
	v_add_u32_e32 v189, v19, v52
	v_add_u32_e32 v190, v23, v53
	v_add_u32_e32 v191, v7, v54
	v_add_u32_e32 v192, v9, v55
	v_add_u32_e32 v193, v15, v56
	v_add_u32_e32 v194, v19, v57
	v_add_u32_e32 v195, v23, v58
	v_add_u32_e32 v196, v7, v59
	v_add_u32_e32 v197, v9, v60
	v_add_u32_e32 v198, v15, v61
	v_add_u32_e32 v199, v19, v62
	v_add_u32_e32 v200, v23, v63
	v_lshlrev_b32_e32 v84, 2, v0
	v_lshlrev_b32_e32 v86, 2, v2
	v_lshlrev_b32_e32 v88, 2, v4
	v_lshlrev_b32_e32 v90, 2, v6
	v_lshlrev_b32_e32 v92, 2, v8
	v_lshlrev_b32_e32 v94, 2, v10
	v_lshlrev_b32_e32 v96, 2, v12
	v_lshlrev_b32_e32 v98, 2, v14
	v_lshlrev_b32_e32 v100, 2, v16
	v_lshlrev_b32_e32 v102, 2, v18
	v_lshlrev_b32_e32 v104, 2, v20
	v_lshlrev_b32_e32 v106, 2, v22
	v_lshlrev_b32_e32 v108, 2, v24
	v_lshlrev_b32_e32 v110, 2, v26
	v_lshlrev_b32_e32 v112, 2, v28
	v_lshlrev_b32_e32 v114, 2, v30
	s_mov_b32 s39, s33
	s_branch .LBB0_339

.LBB0_388:
	s_cmp_eq_u32 s94, 1
	s_cbranch_scc1 .Lmy_p2_done
	v_lshl_add_u32 v0, s33, 9, v158
	v_ashrrev_i32_e32 v0, 3, v0
	s_mov_b32 s18, 0x40000
	v_cmp_gt_i32_e32 vcc, s18, v0
	s_and_saveexec_b64 s[14:15], vcc
	s_cbranch_execz .LBB0_461
	s_waitcnt lgkmcnt(0)
	v_mbcnt_lo_u32_b32 v3, -1, 0
	v_mbcnt_hi_u32_b32 v3, -1, v3
	v_and_b32_e32 v5, 64, v3
	v_xor_b32_e32 v4, 1, v3
	v_add_u32_e32 v5, 64, v5
	v_cmp_lt_i32_e32 vcc, v4, v5
	v_exp_f32_e32 v36, 0xc01773da
	v_exp_f32_e32 v37, 0xc09773da
	v_cndmask_b32_e32 v4, v3, v4, vcc
	v_lshlrev_b32_e32 v43, 2, v4
	v_xor_b32_e32 v4, 2, v3
	v_cmp_lt_i32_e32 vcc, v4, v5
	v_exp_f32_e32 v38, 0xc0e32dc6
	v_exp_f32_e32 v39, 0xc11773da
	v_cndmask_b32_e32 v4, v3, v4, vcc
	v_exp_f32_e32 v40, 0xc13d50d1
	v_exp_f32_e32 v41, 0xc1632dc6
	v_exp_f32_e32 v42, 0xc184855f
	v_and_b32_e32 v1, 7, v158
	v_lshlrev_b32_e32 v44, 2, v4
	v_xor_b32_e32 v4, 4, v3
	v_lshlrev_b32_e32 v2, 3, v1
	v_cmp_lt_i32_e32 vcc, v4, v5
	s_and_b32 s2, s88, 0x7fffff
	s_lshl_b32 s0, s88, 6
	v_mov_b32_e32 v13, 0
	v_cndmask_b32_e32 v3, v3, v4, vcc
	s_lshl_b32 s2, s2, 7
	v_lshlrev_b32_e32 v16, 2, v2
	s_and_b32 s19, s0, 0x1fffffc0
	v_lshlrev_b32_e32 v45, 2, v3
	v_cmp_gt_u32_e32 vcc, 2, v1
	v_cmp_eq_u32_e64 s[0:1], 0, v1
	v_lshlrev_b32_e32 v46, 6, v0
	s_lshl_b32 s20, s88, 14
	s_sub_i32 s21, 0, s2
	s_mov_b64 s[16:17], 0
	s_mov_b32 s22, 0x20000
	v_mov_b32_e32 v47, 0x1000
	v_lshlrev_b32_e32 v14, 1, v2
	v_mov_b32_e32 v15, v13
	s_mov_b32 s23, 0x3ffff
	v_mov_b32_e32 v48, s61
	v_mov_b32_e32 v49, s59
	v_mov_b32_e32 v50, s60
	v_mov_b32_e32 v51, s58
	v_mov_b32_e32 v18, v16
	v_mov_b32_e32 v19, v13
	v_mov_b32_e32 v52, 0x358637bd
	s_mov_b32 s24, 0x800000
	v_mov_b32_e32 v53, 0x3e000000
	s_branch .LBB0_391

.LBB0_461:
	s_or_b64 exec, exec, s[14:15]
	s_cmp_eq_u32 s94, 0
	s_cbranch_scc0 .Lmy_p2_done
	s_mov_b32 s94, 1
	s_waitcnt vmcnt(0) lgkmcnt(0)
	s_branch .Lmy_p2_pre
.Lmy_p2_done:
	s_cmp_lt_i32 s87, 4
	s_cbranch_scc1 .LBB0_515
	s_waitcnt vmcnt(0)
	s_waitcnt lgkmcnt(0)
	s_barrier
	s_mov_b64 s[0:1], exec
	v_readlane_b32 s2, v252, 5
	v_readlane_b32 s3, v252, 6
	s_and_b64 s[2:3], s[0:1], s[2:3]
	s_mov_b64 exec, s[2:3]
	s_cbranch_execz .LBB0_514
	s_add_i32 s2, 0, 0x25fc0
	v_mov_b32_e32 v0, s2
	s_waitcnt vmcnt(0) expcnt(0) lgkmcnt(0)
	ds_read_b32 v2, v0
	s_add_i32 s2, 0, 0x25fc4
	v_mov_b32_e32 v0, s2
	ds_read_b32 v0, v0
	s_waitcnt lgkmcnt(1)
	v_cmp_ne_u32_e32 vcc, 0, v2
	s_cbranch_vccnz .LBB0_478
	v_readlane_b32 s2, v252, 0
	v_readlane_b32 s3, v252, 1
	s_load_dwordx2 s[6:7], s[2:3], 0x4
	s_add_u32 s2, s84, 0x5900200
	s_addc_u32 s3, s85, 0
	s_add_u32 s4, s84, 0x5900400
	s_addc_u32 s5, s85, 0
	s_waitcnt lgkmcnt(0)
	s_mul_i32 s44, s6, s88
	s_add_u32 s6, s84, 0x5900500
	s_mul_i32 s44, s44, s7
	s_addc_u32 s7, s85, 0
	s_add_u32 s8, s84, 0x5900600
	s_addc_u32 s9, s85, 0
	s_add_u32 s10, s84, 0x5900700
	s_addc_u32 s11, s85, 0
	s_add_u32 s12, s84, 0x5900800
	s_addc_u32 s13, s85, 0
	s_add_u32 s14, s84, 0x5900900
	s_addc_u32 s15, s85, 0
	s_add_u32 s16, s84, 0x5900a00
	s_addc_u32 s17, s85, 0
	s_add_u32 s18, s84, 0x5900b00
	s_addc_u32 s19, s85, 0
	s_add_u32 s20, s84, 0x5900c00
	s_addc_u32 s21, s85, 0
	s_add_u32 s22, s84, 0x5900d00
	s_addc_u32 s23, s85, 0
	s_add_u32 s24, s84, 0x5900e00
	s_addc_u32 s25, s85, 0
	s_add_u32 s26, s84, 0x5900f00
	s_addc_u32 s27, s85, 0
	s_add_u32 s28, s84, 0x5901000
	s_addc_u32 s29, s85, 0
	s_add_u32 s30, s84, 0x5901100
	s_addc_u32 s31, s85, 0
	s_add_u32 s34, s84, 0x5901200
	s_addc_u32 s35, s85, 0
	s_add_u32 s36, s84, 0x5901300
	s_addc_u32 s37, s85, 0
	s_mov_b32 s45, 1
	v_mov_b32_e32 v16, 0
	s_branch .LBB0_466
